# up-projection K-loop: 4 LDS-DMA per phase instead of 2/6/2/6, waits re-derived
# speedup vs baseline: 1.0026x; 1.0026x over previous
.LBB0_363:
	s_add_u32 s34, s30, 0xfffc0080
	s_addc_u32 s35, s31, -1
	s_add_i32 s57, 0, 0x10000
	s_cmp_eq_u32 s56, 12
	s_cselect_b32 s37, s23, s35
	s_cselect_b32 s36, s39, s34
	v_add_u32_e32 v146, s57, v155
	s_cselect_b32 s35, s21, s43
	s_cselect_b32 s34, s40, s41
	s_add_i32 s60, 0, 0x14000
	ds_read_b128 v[142:145], v146
	ds_read_b128 v[168:171], v146 offset:1024
	ds_read_b128 v[172:175], v146 offset:2048
	ds_read_b128 v[176:179], v146 offset:3072
	v_add_u32_e32 v146, s60, v155
	ds_read_b128 v[180:183], v146
	ds_read_b128 v[184:187], v146 offset:1024
	ds_read_b128 v[188:191], v146 offset:2048
	ds_read_b128 v[192:195], v146 offset:3072
	s_add_u32 s100, s30, 0xfffc0000
	s_addc_u32 s101, s31, -1
	s_mov_b32 m0, s52
	ds_read_b128 v[196:199], v157
	ds_read_b128 v[200:203], v157 offset:1024
	ds_read_b128 v[204:207], v157 offset:2048
	ds_read_b128 v[220:223], v157 offset:3072
	ds_read_b128 v[236:239], v157 offset:4096
	ds_read_b128 v[240:243], v157 offset:5120
	ds_read_b128 v[244:247], v157 offset:6144
	ds_read_b128 v[248:251], v157 offset:7168
	global_load_lds_dwordx4 v140, s[100:101]
	s_mov_b32 m0, s53
	s_nop 0
	global_load_lds_dwordx4 v138, s[100:101]
	s_add_i32 m0, s48, 0xc000
	s_nop 0
	global_load_lds_dwordx4 v140, s[30:31]
	s_add_i32 m0, s48, 0xe000
	s_nop 0
	global_load_lds_dwordx4 v138, s[30:31]
	s_waitcnt vmcnt(8)
	s_waitcnt lgkmcnt(0)
	s_barrier
	s_waitcnt lgkmcnt(0)
	v_mfma_f32_16x16x32_bf16 v[126:129], v[142:145], v[196:199], v[126:129]
	v_mfma_f32_16x16x32_bf16 v[118:121], v[172:175], v[196:199], v[118:121]
	v_mfma_f32_16x16x32_bf16 v[110:113], v[142:145], v[204:207], v[110:113]
	v_mfma_f32_16x16x32_bf16 v[102:105], v[172:175], v[204:207], v[102:105]
	v_mfma_f32_16x16x32_bf16 v[94:97], v[142:145], v[236:239], v[94:97]
	v_mfma_f32_16x16x32_bf16 v[86:89], v[172:175], v[236:239], v[86:89]
	v_mfma_f32_16x16x32_bf16 v[78:81], v[142:145], v[244:247], v[78:81]
	v_mfma_f32_16x16x32_bf16 v[70:73], v[172:175], v[244:247], v[70:73]
	v_mfma_f32_16x16x32_bf16 v[126:129], v[168:171], v[200:203], v[126:129]
	v_mfma_f32_16x16x32_bf16 v[118:121], v[176:179], v[200:203], v[118:121]
	v_mfma_f32_16x16x32_bf16 v[110:113], v[168:171], v[220:223], v[110:113]
	v_mfma_f32_16x16x32_bf16 v[102:105], v[176:179], v[220:223], v[102:105]
	v_mfma_f32_16x16x32_bf16 v[94:97], v[168:171], v[240:243], v[94:97]
	v_mfma_f32_16x16x32_bf16 v[86:89], v[176:179], v[240:243], v[86:89]
	v_mfma_f32_16x16x32_bf16 v[78:81], v[168:171], v[248:251], v[78:81]
	v_mfma_f32_16x16x32_bf16 v[70:73], v[176:179], v[248:251], v[70:73]
	v_mfma_f32_16x16x32_bf16 v[122:125], v[180:183], v[196:199], v[122:125]
	v_mfma_f32_16x16x32_bf16 v[114:117], v[188:191], v[196:199], v[114:117]
	v_mfma_f32_16x16x32_bf16 v[106:109], v[180:183], v[204:207], v[106:109]
	v_mfma_f32_16x16x32_bf16 v[98:101], v[188:191], v[204:207], v[98:101]
	v_mfma_f32_16x16x32_bf16 v[90:93], v[180:183], v[236:239], v[90:93]
	v_mfma_f32_16x16x32_bf16 v[82:85], v[188:191], v[236:239], v[82:85]
	v_mfma_f32_16x16x32_bf16 v[74:77], v[180:183], v[244:247], v[74:77]
	v_mfma_f32_16x16x32_bf16 v[66:69], v[188:191], v[244:247], v[66:69]
	v_mfma_f32_16x16x32_bf16 v[122:125], v[184:187], v[200:203], v[122:125]
	v_mfma_f32_16x16x32_bf16 v[114:117], v[192:195], v[200:203], v[114:117]
	v_mfma_f32_16x16x32_bf16 v[106:109], v[184:187], v[220:223], v[106:109]
	v_mfma_f32_16x16x32_bf16 v[98:101], v[192:195], v[220:223], v[98:101]
	v_mfma_f32_16x16x32_bf16 v[90:93], v[184:187], v[240:243], v[90:93]
	v_mfma_f32_16x16x32_bf16 v[82:85], v[192:195], v[240:243], v[82:85]
	v_mfma_f32_16x16x32_bf16 v[74:77], v[184:187], v[248:251], v[74:77]
	v_mfma_f32_16x16x32_bf16 v[66:69], v[192:195], v[248:251], v[66:69]
	s_barrier
	s_add_i32 s57, s57, s44
	s_mov_b32 m0, s57
	ds_read_b128 v[196:199], v157 offset:16384
	ds_read_b128 v[200:203], v157 offset:17408
	ds_read_b128 v[204:207], v157 offset:18432
	ds_read_b128 v[220:223], v157 offset:19456
	ds_read_b128 v[236:239], v157 offset:20480
	ds_read_b128 v[240:243], v157 offset:21504
	ds_read_b128 v[244:247], v157 offset:22528
	ds_read_b128 v[248:251], v157 offset:23552
	global_load_lds_dwordx4 v134, s[34:35]
	s_add_i32 m0, s57, 0x2000
	s_add_u32 s58, s34, 0x40000
	s_addc_u32 s59, s35, 0
	s_add_i32 s57, s60, s44
	global_load_lds_dwordx4 v130, s[34:35]
	s_mov_b32 m0, s57
	s_nop 0
	global_load_lds_dwordx4 v134, s[58:59]
	s_add_i32 m0, s57, 0x2000
	s_nop 0
	global_load_lds_dwordx4 v130, s[58:59]
	s_waitcnt vmcnt(6)
	s_waitcnt lgkmcnt(0)
	s_barrier
	s_waitcnt lgkmcnt(0)
	v_mfma_f32_16x16x32_bf16 v[62:65], v[142:145], v[196:199], v[62:65]
	v_mfma_f32_16x16x32_bf16 v[54:57], v[172:175], v[196:199], v[54:57]
	v_mfma_f32_16x16x32_bf16 v[46:49], v[142:145], v[204:207], v[46:49]
	v_mfma_f32_16x16x32_bf16 v[38:41], v[172:175], v[204:207], v[38:41]
	v_mfma_f32_16x16x32_bf16 v[30:33], v[142:145], v[236:239], v[30:33]
	v_mfma_f32_16x16x32_bf16 v[22:25], v[172:175], v[236:239], v[22:25]
	v_mfma_f32_16x16x32_bf16 v[14:17], v[142:145], v[244:247], v[14:17]
	v_mfma_f32_16x16x32_bf16 v[6:9], v[172:175], v[244:247], v[6:9]
	v_mfma_f32_16x16x32_bf16 v[62:65], v[168:171], v[200:203], v[62:65]
	v_mfma_f32_16x16x32_bf16 v[54:57], v[176:179], v[200:203], v[54:57]
	v_mfma_f32_16x16x32_bf16 v[46:49], v[168:171], v[220:223], v[46:49]
	v_mfma_f32_16x16x32_bf16 v[38:41], v[176:179], v[220:223], v[38:41]
	v_mfma_f32_16x16x32_bf16 v[30:33], v[168:171], v[240:243], v[30:33]
	v_mfma_f32_16x16x32_bf16 v[22:25], v[176:179], v[240:243], v[22:25]
	v_mfma_f32_16x16x32_bf16 v[14:17], v[168:171], v[248:251], v[14:17]
	v_mfma_f32_16x16x32_bf16 v[6:9], v[176:179], v[248:251], v[6:9]
	v_mfma_f32_16x16x32_bf16 v[58:61], v[180:183], v[196:199], v[58:61]
	v_mfma_f32_16x16x32_bf16 v[50:53], v[188:191], v[196:199], v[50:53]
	v_mfma_f32_16x16x32_bf16 v[42:45], v[180:183], v[204:207], v[42:45]
	v_mfma_f32_16x16x32_bf16 v[34:37], v[188:191], v[204:207], v[34:37]
	v_mfma_f32_16x16x32_bf16 v[26:29], v[180:183], v[236:239], v[26:29]
	v_mfma_f32_16x16x32_bf16 v[18:21], v[188:191], v[236:239], v[18:21]
	v_mfma_f32_16x16x32_bf16 v[10:13], v[180:183], v[244:247], v[10:13]
	v_mfma_f32_16x16x32_bf16 v[2:5], v[188:191], v[244:247], v[2:5]
	v_mfma_f32_16x16x32_bf16 v[58:61], v[184:187], v[200:203], v[58:61]
	v_mfma_f32_16x16x32_bf16 v[50:53], v[192:195], v[200:203], v[50:53]
	v_mfma_f32_16x16x32_bf16 v[42:45], v[184:187], v[220:223], v[42:45]
	v_mfma_f32_16x16x32_bf16 v[34:37], v[192:195], v[220:223], v[34:37]
	v_mfma_f32_16x16x32_bf16 v[26:29], v[184:187], v[240:243], v[26:29]
	v_mfma_f32_16x16x32_bf16 v[18:21], v[192:195], v[240:243], v[18:21]
	v_mfma_f32_16x16x32_bf16 v[10:13], v[184:187], v[248:251], v[10:13]
	v_mfma_f32_16x16x32_bf16 v[2:5], v[192:195], v[248:251], v[2:5]
	s_barrier
	s_add_i32 s57, 0, 0x18000
	v_add_u32_e32 v164, s57, v155
	s_add_i32 s58, 0, 0x1c000
	ds_read_b128 v[142:145], v164
	ds_read_b128 v[168:171], v164 offset:1024
	ds_read_b128 v[172:175], v164 offset:2048
	ds_read_b128 v[176:179], v164 offset:3072
	v_add_u32_e32 v164, s58, v155
	ds_read_b128 v[180:183], v164
	ds_read_b128 v[184:187], v164 offset:1024
	ds_read_b128 v[188:191], v164 offset:2048
	ds_read_b128 v[192:195], v164 offset:3072
	s_mov_b32 m0, s48
	s_nop 0
	global_load_lds_dwordx4 v136, s[36:37]
	s_mov_b32 m0, s49
	s_nop 0
	global_load_lds_dwordx4 v132, s[36:37]
	s_add_u32 s36, s36, 0x40000
	s_addc_u32 s37, s37, 0
	s_mov_b32 m0, s50
	ds_read_b128 v[196:199], v157 offset:32768
	ds_read_b128 v[200:203], v157 offset:33792
	ds_read_b128 v[204:207], v157 offset:34816
	ds_read_b128 v[220:223], v157 offset:35840
	ds_read_b128 v[236:239], v157 offset:36864
	ds_read_b128 v[240:243], v157 offset:37888
	ds_read_b128 v[244:247], v157 offset:38912
	ds_read_b128 v[248:251], v157 offset:39936
	global_load_lds_dwordx4 v136, s[36:37]
	s_mov_b32 m0, s51
	s_nop 0
	global_load_lds_dwordx4 v132, s[36:37]
	s_waitcnt vmcnt(8)
	s_waitcnt lgkmcnt(0)
	s_barrier
	s_waitcnt lgkmcnt(0)
	v_mfma_f32_16x16x32_bf16 v[126:129], v[142:145], v[196:199], v[126:129]
	v_mfma_f32_16x16x32_bf16 v[118:121], v[172:175], v[196:199], v[118:121]
	v_mfma_f32_16x16x32_bf16 v[110:113], v[142:145], v[204:207], v[110:113]
	v_mfma_f32_16x16x32_bf16 v[102:105], v[172:175], v[204:207], v[102:105]
	v_mfma_f32_16x16x32_bf16 v[94:97], v[142:145], v[236:239], v[94:97]
	v_mfma_f32_16x16x32_bf16 v[86:89], v[172:175], v[236:239], v[86:89]
	v_mfma_f32_16x16x32_bf16 v[78:81], v[142:145], v[244:247], v[78:81]
	v_mfma_f32_16x16x32_bf16 v[70:73], v[172:175], v[244:247], v[70:73]
	v_mfma_f32_16x16x32_bf16 v[126:129], v[168:171], v[200:203], v[126:129]
	v_mfma_f32_16x16x32_bf16 v[118:121], v[176:179], v[200:203], v[118:121]
	v_mfma_f32_16x16x32_bf16 v[110:113], v[168:171], v[220:223], v[110:113]
	v_mfma_f32_16x16x32_bf16 v[102:105], v[176:179], v[220:223], v[102:105]
	v_mfma_f32_16x16x32_bf16 v[94:97], v[168:171], v[240:243], v[94:97]
	v_mfma_f32_16x16x32_bf16 v[86:89], v[176:179], v[240:243], v[86:89]
	v_mfma_f32_16x16x32_bf16 v[78:81], v[168:171], v[248:251], v[78:81]
	v_mfma_f32_16x16x32_bf16 v[70:73], v[176:179], v[248:251], v[70:73]
	v_mfma_f32_16x16x32_bf16 v[122:125], v[180:183], v[196:199], v[122:125]
	v_mfma_f32_16x16x32_bf16 v[114:117], v[188:191], v[196:199], v[114:117]
	v_mfma_f32_16x16x32_bf16 v[106:109], v[180:183], v[204:207], v[106:109]
	v_mfma_f32_16x16x32_bf16 v[98:101], v[188:191], v[204:207], v[98:101]
	v_mfma_f32_16x16x32_bf16 v[90:93], v[180:183], v[236:239], v[90:93]
	v_mfma_f32_16x16x32_bf16 v[82:85], v[188:191], v[236:239], v[82:85]
	v_mfma_f32_16x16x32_bf16 v[74:77], v[180:183], v[244:247], v[74:77]
	v_mfma_f32_16x16x32_bf16 v[66:69], v[188:191], v[244:247], v[66:69]
	v_mfma_f32_16x16x32_bf16 v[122:125], v[184:187], v[200:203], v[122:125]
	v_mfma_f32_16x16x32_bf16 v[114:117], v[192:195], v[200:203], v[114:117]
	v_mfma_f32_16x16x32_bf16 v[106:109], v[184:187], v[220:223], v[106:109]
	v_mfma_f32_16x16x32_bf16 v[98:101], v[192:195], v[220:223], v[98:101]
	v_mfma_f32_16x16x32_bf16 v[90:93], v[184:187], v[240:243], v[90:93]
	v_mfma_f32_16x16x32_bf16 v[82:85], v[192:195], v[240:243], v[82:85]
	v_mfma_f32_16x16x32_bf16 v[74:77], v[184:187], v[248:251], v[74:77]
	v_mfma_f32_16x16x32_bf16 v[66:69], v[192:195], v[248:251], v[66:69]
	s_barrier
	s_add_i32 s36, s57, s44
	s_add_u32 s34, s34, 0x80
	s_mov_b32 m0, s36
	s_addc_u32 s35, s35, 0
	ds_read_b128 v[196:199], v157 offset:49152
	ds_read_b128 v[200:203], v157 offset:50176
	ds_read_b128 v[204:207], v157 offset:51200
	ds_read_b128 v[220:223], v157 offset:52224
	ds_read_b128 v[236:239], v157 offset:53248
	ds_read_b128 v[240:243], v157 offset:54272
	ds_read_b128 v[244:247], v157 offset:55296
	ds_read_b128 v[248:251], v157 offset:56320
	global_load_lds_dwordx4 v134, s[34:35]
	s_add_i32 m0, s36, 0x2000
	s_add_i32 s36, s58, s44
	global_load_lds_dwordx4 v130, s[34:35]
	s_mov_b32 m0, s36
	s_add_u32 s34, s34, 0x40000
	s_addc_u32 s35, s35, 0
	global_load_lds_dwordx4 v134, s[34:35]
	s_add_i32 m0, s36, 0x2000
	s_nop 0
	global_load_lds_dwordx4 v130, s[34:35]
	s_waitcnt vmcnt(6)
	s_waitcnt lgkmcnt(0)
	s_barrier
	s_waitcnt lgkmcnt(0)
	v_mfma_f32_16x16x32_bf16 v[62:65], v[142:145], v[196:199], v[62:65]
	v_mfma_f32_16x16x32_bf16 v[54:57], v[172:175], v[196:199], v[54:57]
	v_mfma_f32_16x16x32_bf16 v[46:49], v[142:145], v[204:207], v[46:49]
	v_mfma_f32_16x16x32_bf16 v[38:41], v[172:175], v[204:207], v[38:41]
	v_mfma_f32_16x16x32_bf16 v[30:33], v[142:145], v[236:239], v[30:33]
	v_mfma_f32_16x16x32_bf16 v[22:25], v[172:175], v[236:239], v[22:25]
	v_mfma_f32_16x16x32_bf16 v[14:17], v[142:145], v[244:247], v[14:17]
	v_mfma_f32_16x16x32_bf16 v[6:9], v[172:175], v[244:247], v[6:9]
	v_mfma_f32_16x16x32_bf16 v[62:65], v[168:171], v[200:203], v[62:65]
	v_mfma_f32_16x16x32_bf16 v[54:57], v[176:179], v[200:203], v[54:57]
	v_mfma_f32_16x16x32_bf16 v[46:49], v[168:171], v[220:223], v[46:49]
	v_mfma_f32_16x16x32_bf16 v[38:41], v[176:179], v[220:223], v[38:41]
	v_mfma_f32_16x16x32_bf16 v[30:33], v[168:171], v[240:243], v[30:33]
	v_mfma_f32_16x16x32_bf16 v[22:25], v[176:179], v[240:243], v[22:25]
	v_mfma_f32_16x16x32_bf16 v[14:17], v[168:171], v[248:251], v[14:17]
	v_mfma_f32_16x16x32_bf16 v[6:9], v[176:179], v[248:251], v[6:9]
	v_mfma_f32_16x16x32_bf16 v[58:61], v[180:183], v[196:199], v[58:61]
	v_mfma_f32_16x16x32_bf16 v[50:53], v[188:191], v[196:199], v[50:53]
	v_mfma_f32_16x16x32_bf16 v[42:45], v[180:183], v[204:207], v[42:45]
	v_mfma_f32_16x16x32_bf16 v[34:37], v[188:191], v[204:207], v[34:37]
	v_mfma_f32_16x16x32_bf16 v[26:29], v[180:183], v[236:239], v[26:29]
	v_mfma_f32_16x16x32_bf16 v[18:21], v[188:191], v[236:239], v[18:21]
	v_mfma_f32_16x16x32_bf16 v[10:13], v[180:183], v[244:247], v[10:13]
	v_mfma_f32_16x16x32_bf16 v[2:5], v[188:191], v[244:247], v[2:5]
	v_mfma_f32_16x16x32_bf16 v[58:61], v[184:187], v[200:203], v[58:61]
	v_mfma_f32_16x16x32_bf16 v[50:53], v[192:195], v[200:203], v[50:53]
	v_mfma_f32_16x16x32_bf16 v[42:45], v[184:187], v[220:223], v[42:45]
	v_mfma_f32_16x16x32_bf16 v[34:37], v[192:195], v[220:223], v[34:37]
	v_mfma_f32_16x16x32_bf16 v[26:29], v[184:187], v[240:243], v[26:29]
	v_mfma_f32_16x16x32_bf16 v[18:21], v[192:195], v[240:243], v[18:21]
	v_mfma_f32_16x16x32_bf16 v[10:13], v[184:187], v[248:251], v[10:13]
	v_mfma_f32_16x16x32_bf16 v[2:5], v[192:195], v[248:251], v[2:5]
	s_barrier
	s_add_i32 s56, s56, 2
	s_add_u32 s41, s41, 0x100
	s_addc_u32 s43, s43, 0
	s_add_u32 s30, s30, 0x100
	s_addc_u32 s31, s31, 0
	s_cmp_gt_u32 s56, 13
	s_cbranch_scc0 .LBB0_363
	s_and_b64 vcc, exec, s[16:17]
	s_cbranch_vccz .LBB0_366
	s_barrier
